# s5_out tile loop: back-edge copy of the head with waits that leave the 4 younger Y stores in flight (padded to 128 B to keep later code placement)
# baseline (speedup 1.0000x reference)
; #define LAS __attribute__((address_space(3)))
; __device__ __forceinline__ unsigned pk2(float lo, float hi) { f32x2_t v = {lo, hi}; bf16x2_t b = __builtin_convertvector(v, bf16x2_t); return __builtin_bit_cast(unsigned, b); }
; __device__ __forceinline__ float bflo(unsigned w) { return __uint_as_float(w << 16); }
; __device__ __forceinline__ float bfhi(unsigned w) { return __uint_as_float(w & 0xffff0000u); }
; __device__ __forceinline__ void s5_out_block2(LAS unsigned char* lds, const bf16* __restrict__ MLAG, const bf16* __restrict__ WC, const bf16* __restrict__ HP, const bf16* __restrict__ U, ...
;     ...
;             const int c = ct * 32 + r;
; #pragma unroll
;             for (int ep = 0; ep < 2; ++ep) {
;                 const int j = 2 * jj + ep, t = c * 32 + j;
;                 unsigned pk[2][2];
; #pragma unroll
;                 for (int q2 = 0; q2 < 2; ++q2) {
;                     const int eg = 2 * ep + q2, p0 = 8 * q2 + 4 * h;
;                     const u32x2 uw = *(const LAS u32x2*)(lds + UOFF + r * UROW + j * 32 + p0 * 2);
;                     const f32x4 d = q2 ? dB : dA;
;                     const float y0 = gelu_tanh(acc[4 * eg + 0] + d[0] * bflo(uw.x)), y1 = gelu_tanh(acc[4 * eg + 1] + d[1] * bfhi(uw.x));
;                     const float y2 = gelu_tanh(acc[4 * eg + 2] + d[2] * bflo(uw.y)), y3 = gelu_tanh(acc[4 * eg + 3] + d[3] * bfhi(uw.y));
;                     pk[q2][0] = pk2(y0, y1); pk[q2][1] = pk2(y2, y3);
;                 }
;                 { auto rx = __builtin_amdgcn_permlane32_swap(pk[0][0], pk[1][0], false, false); pk[0][0] = rx[0]; pk[1][0] = rx[1]; }
;                 { auto ry = __builtin_amdgcn_permlane32_swap(pk[0][1], pk[1][1], false, false); pk[0][1] = ry[0]; pk[1][1] = ry[1]; }
.LBB0_804:
	v_add_u32_e32 v1, s20, v163
	v_add_u32_e32 v1, 0x4000, v1
	ds_read2_b64 v[2:5], v1 offset1:2
	s_add_i32 s3, s3, 1
	s_cmp_eq_u32 s3, 4
	s_waitcnt lgkmcnt(0)
	v_lshlrev_b32_e32 v6, 16, v2
	v_and_b32_e32 v7, 0xffff0000, v2
	s_nop 1
	v_pk_fma_f32 v[6:7], v[32:33], v[6:7], v[16:17]
	s_nop 0
	v_mul_f32_e32 v1, 0x3d372713, v6
	v_mul_f32_e32 v2, 0x3d372713, v7
	v_mul_f32_e32 v1, v6, v1
	v_mul_f32_e32 v2, v7, v2
	v_fma_f32 v1, v6, v1, v6
	v_fma_f32 v2, v7, v2, v7
	v_mul_f32_e32 v1, 0x3f4c422a, v1
	v_add_f32_e32 v1, v1, v1
	v_mul_f32_e32 v2, 0x3f4c422a, v2
	v_mul_f32_e32 v1, 0x3fb8aa3b, v1
	v_add_f32_e32 v2, v2, v2
	v_exp_f32_e32 v1, v1
	v_mul_f32_e32 v2, 0x3fb8aa3b, v2
	v_exp_f32_e32 v2, v2
	v_pk_mul_f32 v[6:7], v[6:7], 0.5 op_sel_hi:[1,0]
	v_add_f32_e32 v1, 1.0, v1
	v_rcp_f32_e32 v8, v1
	v_add_f32_e32 v1, 1.0, v2
	v_lshlrev_b32_e32 v2, 16, v3
	v_and_b32_e32 v3, 0xffff0000, v3
	v_pk_fma_f32 v[2:3], v[34:35], v[2:3], v[18:19]
	v_rcp_f32_e32 v9, v1
	v_mul_f32_e32 v1, 0x3d372713, v2
	v_mul_f32_e32 v1, v2, v1
	v_mul_f32_e32 v10, 0x3d372713, v3
	v_fma_f32 v1, v2, v1, v2
	v_mul_f32_e32 v10, v3, v10
	v_mul_f32_e32 v1, 0x3f4c422a, v1
	v_fma_f32 v10, v3, v10, v3
	v_add_f32_e32 v1, v1, v1
	v_mul_f32_e32 v10, 0x3f4c422a, v10
	v_mul_f32_e32 v1, 0x3fb8aa3b, v1
	v_add_f32_e32 v10, v10, v10
	v_exp_f32_e32 v1, v1
	v_mul_f32_e32 v10, 0x3fb8aa3b, v10
	v_exp_f32_e32 v11, v10
	v_pk_fma_f32 v[8:9], v[8:9], 2.0, 1.0 op_sel_hi:[1,0,0] neg_lo:[1,0,0] neg_hi:[1,0,0]
	v_add_f32_e32 v1, 1.0, v1
	v_rcp_f32_e32 v10, v1
	v_add_f32_e32 v1, 1.0, v11
	v_rcp_f32_e32 v11, v1
	v_pk_add_f32 v[8:9], v[8:9], 1.0 op_sel_hi:[1,0]
	v_pk_mul_f32 v[2:3], v[2:3], 0.5 op_sel_hi:[1,0]
	v_pk_mul_f32 v[6:7], v[6:7], v[8:9]
	v_pk_fma_f32 v[8:9], v[10:11], 2.0, 1.0 op_sel_hi:[1,0,0] neg_lo:[1,0,0] neg_hi:[1,0,0]
	s_nop 0
	v_pk_add_f32 v[8:9], v[8:9], 1.0 op_sel_hi:[1,0]
	s_nop 0
	v_pk_mul_f32 v[8:9], v[2:3], v[8:9]
	v_cvt_pk_bf16_f32 v2, v6, v7
	v_lshlrev_b32_e32 v6, 16, v4
	v_and_b32_e32 v7, 0xffff0000, v4
	v_pk_fma_f32 v[6:7], v[36:37], v[6:7], v[20:21]
	s_nop 0
	v_mul_f32_e32 v1, 0x3d372713, v6
	v_mul_f32_e32 v1, v6, v1
	v_mul_f32_e32 v3, 0x3d372713, v7
	v_fma_f32 v1, v6, v1, v6
	v_mul_f32_e32 v3, v7, v3
	v_mul_f32_e32 v1, 0x3f4c422a, v1
	v_fma_f32 v3, v7, v3, v7
	v_add_f32_e32 v1, v1, v1
	v_mul_f32_e32 v3, 0x3f4c422a, v3
	v_mul_f32_e32 v1, 0x3fb8aa3b, v1
	v_add_f32_e32 v3, v3, v3
	v_exp_f32_e32 v1, v1
	v_mul_f32_e32 v3, 0x3fb8aa3b, v3
	v_exp_f32_e32 v4, v3
	v_cvt_pk_bf16_f32 v3, v8, v9
	v_add_f32_e32 v1, 1.0, v1
	v_rcp_f32_e32 v8, v1
	v_add_f32_e32 v1, 1.0, v4
	v_lshlrev_b32_e32 v4, 16, v5
	v_and_b32_e32 v5, 0xffff0000, v5
	v_pk_fma_f32 v[4:5], v[38:39], v[4:5], v[22:23]
	v_rcp_f32_e32 v9, v1
	v_mul_f32_e32 v1, 0x3d372713, v4
	v_mul_f32_e32 v1, v4, v1
	v_mul_f32_e32 v10, 0x3d372713, v5
	v_fma_f32 v1, v4, v1, v4
	v_mul_f32_e32 v10, v5, v10
	v_mul_f32_e32 v1, 0x3f4c422a, v1
	v_fma_f32 v10, v5, v10, v5
	v_add_f32_e32 v1, v1, v1
	v_mul_f32_e32 v10, 0x3f4c422a, v10
	v_mul_f32_e32 v1, 0x3fb8aa3b, v1
	v_add_f32_e32 v10, v10, v10
	v_exp_f32_e32 v1, v1
	v_mul_f32_e32 v10, 0x3fb8aa3b, v10
	v_exp_f32_e32 v11, v10
	v_pk_fma_f32 v[8:9], v[8:9], 2.0, 1.0 op_sel_hi:[1,0,0] neg_lo:[1,0,0] neg_hi:[1,0,0]
	v_add_f32_e32 v1, 1.0, v1
	v_rcp_f32_e32 v10, v1
	v_add_f32_e32 v1, 1.0, v11
	v_rcp_f32_e32 v11, v1
	v_pk_mul_f32 v[6:7], v[6:7], 0.5 op_sel_hi:[1,0]
	v_pk_add_f32 v[8:9], v[8:9], 1.0 op_sel_hi:[1,0]
	v_pk_mul_f32 v[4:5], v[4:5], 0.5 op_sel_hi:[1,0]
	v_pk_mul_f32 v[6:7], v[6:7], v[8:9]
	v_pk_fma_f32 v[8:9], v[10:11], 2.0, 1.0 op_sel_hi:[1,0,0] neg_lo:[1,0,0] neg_hi:[1,0,0]
	v_add_u32_e32 v1, s21, v163
	v_pk_add_f32 v[8:9], v[8:9], 1.0 op_sel_hi:[1,0]
	v_add_u32_e32 v1, 0x4000, v1
	v_pk_mul_f32 v[8:9], v[4:5], v[8:9]
	v_cvt_pk_bf16_f32 v4, v6, v7
	v_cvt_pk_bf16_f32 v5, v8, v9
	ds_read2_b64 v[6:9], v1 offset1:2
	v_add_u32_e32 v10, s18, v0
	v_ashrrev_i32_e32 v11, 31, v10
	v_lshlrev_b64 v[10:11], 11, v[10:11]
	v_permlane32_swap_b32_e32 v2, v4
	s_waitcnt lgkmcnt(0)
; #define LAS __attribute__((address_space(3)))
; __device__ __forceinline__ unsigned pk2(float lo, float hi) { f32x2_t v = {lo, hi}; bf16x2_t b = __builtin_convertvector(v, bf16x2_t); return __builtin_bit_cast(unsigned, b); }
; __device__ __forceinline__ float bflo(unsigned w) { return __uint_as_float(w << 16); }
; __device__ __forceinline__ float bfhi(unsigned w) { return __uint_as_float(w & 0xffff0000u); }
; #define LBAR() do { asm volatile("s_waitcnt lgkmcnt(0)" ::: "memory"); __builtin_amdgcn_s_barrier(); asm volatile("" ::: "memory"); } while (0)
; __device__ __forceinline__ void s5_out_block2(LAS unsigned char* lds, const bf16* __restrict__ MLAG, const bf16* __restrict__ WC, const bf16* __restrict__ HP, const bf16* __restrict__ U, ...
;     ...
;         LBAR();
;         {
; #pragma unroll
;           for (int i = 0; i < 4; ++i) { const int idx = tid + 512 * i; *(LAS u32x4*)(lds + UOFF + (idx >> 6) * UROW + (idx & 63) * 16) = su[i]; }
;           *(LAS u32x4*)(lds + HOFF + (tid >> 4) * HROW + (tid & 15) * 16) = sh; }
;         LBAR();
;     ...
;             const int c = ct * 32 + r;
; #pragma unroll
;             for (int ep = 0; ep < 2; ++ep) {
;                 const int j = 2 * jj + ep, t = c * 32 + j;
;                 unsigned pk[2][2];
; #pragma unroll
;                 for (int q2 = 0; q2 < 2; ++q2) {
;                     const int eg = 2 * ep + q2, p0 = 8 * q2 + 4 * h;
;                     const u32x2 uw = *(const LAS u32x2*)(lds + UOFF + r * UROW + j * 32 + p0 * 2);
;                     const f32x4 d = q2 ? dB : dA;
;                     const float y0 = gelu_tanh(acc[4 * eg + 0] + d[0] * bflo(uw.x)), y1 = gelu_tanh(acc[4 * eg + 1] + d[1] * bfhi(uw.x));
;                     const float y2 = gelu_tanh(acc[4 * eg + 2] + d[2] * bflo(uw.y)), y3 = gelu_tanh(acc[4 * eg + 3] + d[3] * bfhi(uw.y));
;                     pk[q2][0] = pk2(y0, y1); pk[q2][1] = pk2(y2, y3);
;                 }
;                 { auto rx = __builtin_amdgcn_permlane32_swap(pk[0][0], pk[1][0], false, false); pk[0][0] = rx[0]; pk[1][0] = rx[1]; }
;                 { auto ry = __builtin_amdgcn_permlane32_swap(pk[0][1], pk[1][1], false, false); pk[0][1] = ry[0]; pk[1][1] = ry[1]; }
;                 u32x4 o = {pk[0][0], pk[0][1], pk[1][0], pk[1][1]};
;                 *(u32x4*)(Y + (size_t)t * 1024 + g * 16 + 8 * h) = o;
;             }
	v_lshlrev_b32_e32 v12, 16, v6
	v_and_b32_e32 v13, 0xffff0000, v6
	v_pk_fma_f32 v[12:13], v[32:33], v[12:13], v[24:25]
	v_permlane32_swap_b32_e32 v3, v5
	v_mul_f32_e32 v1, 0x3d372713, v12
	v_mul_f32_e32 v1, v12, v1
	v_mul_f32_e32 v6, 0x3d372713, v13
	v_fma_f32 v1, v12, v1, v12
	v_mul_f32_e32 v6, v13, v6
	v_mul_f32_e32 v1, 0x3f4c422a, v1
	v_fma_f32 v6, v13, v6, v13
	v_add_f32_e32 v1, v1, v1
	v_mul_f32_e32 v6, 0x3f4c422a, v6
	v_mul_f32_e32 v1, 0x3fb8aa3b, v1
	v_add_f32_e32 v6, v6, v6
	v_exp_f32_e32 v1, v1
	v_mul_f32_e32 v6, 0x3fb8aa3b, v6
	v_exp_f32_e32 v6, v6
	v_lshl_add_u64 v[10:11], v[156:157], 0, v[10:11]
	global_store_dwordx4 v[10:11], v[2:5], off
	v_add_f32_e32 v1, 1.0, v1
	v_pk_mul_f32 v[10:11], v[12:13], 0.5 op_sel_hi:[1,0]
	v_lshlrev_b32_e32 v4, 16, v7
	v_and_b32_e32 v5, 0xffff0000, v7
	v_rcp_f32_e32 v2, v1
	v_add_f32_e32 v1, 1.0, v6
	v_pk_fma_f32 v[4:5], v[34:35], v[4:5], v[26:27]
	v_rcp_f32_e32 v3, v1
	v_mul_f32_e32 v1, 0x3d372713, v4
	v_mul_f32_e32 v1, v4, v1
	v_mul_f32_e32 v6, 0x3d372713, v5
	v_fma_f32 v1, v4, v1, v4
	v_mul_f32_e32 v6, v5, v6
	v_mul_f32_e32 v1, 0x3f4c422a, v1
	v_fma_f32 v6, v5, v6, v5
	v_add_f32_e32 v1, v1, v1
	v_mul_f32_e32 v6, 0x3f4c422a, v6
	v_mul_f32_e32 v1, 0x3fb8aa3b, v1
	v_add_f32_e32 v6, v6, v6
	v_exp_f32_e32 v1, v1
	v_mul_f32_e32 v6, 0x3fb8aa3b, v6
	v_exp_f32_e32 v7, v6
	v_pk_mul_f32 v[4:5], v[4:5], 0.5 op_sel_hi:[1,0]
	v_add_f32_e32 v1, 1.0, v1
	v_rcp_f32_e32 v6, v1
	v_add_f32_e32 v1, 1.0, v7
	v_rcp_f32_e32 v7, v1
	v_pk_fma_f32 v[2:3], v[2:3], 2.0, 1.0 op_sel_hi:[1,0,0] neg_lo:[1,0,0] neg_hi:[1,0,0]
	v_add_u32_e32 v0, s19, v0
	v_pk_add_f32 v[2:3], v[2:3], 1.0 op_sel_hi:[1,0]
	v_pk_fma_f32 v[6:7], v[6:7], 2.0, 1.0 op_sel_hi:[1,0,0] neg_lo:[1,0,0] neg_hi:[1,0,0]
	v_pk_mul_f32 v[2:3], v[10:11], v[2:3]
	v_pk_add_f32 v[6:7], v[6:7], 1.0 op_sel_hi:[1,0]
	v_cvt_pk_bf16_f32 v2, v2, v3
	v_pk_mul_f32 v[4:5], v[4:5], v[6:7]
	v_lshlrev_b32_e32 v6, 16, v8
	v_and_b32_e32 v7, 0xffff0000, v8
	v_pk_fma_f32 v[6:7], v[36:37], v[6:7], v[28:29]
	s_nop 0
	v_mul_f32_e32 v1, 0x3d372713, v6
	v_mul_f32_e32 v1, v6, v1
	v_mul_f32_e32 v3, 0x3d372713, v7
	v_fma_f32 v1, v6, v1, v6
	v_mul_f32_e32 v3, v7, v3
	v_mul_f32_e32 v1, 0x3f4c422a, v1
	v_fma_f32 v3, v7, v3, v7
	v_add_f32_e32 v1, v1, v1
	v_mul_f32_e32 v3, 0x3f4c422a, v3
	v_mul_f32_e32 v1, 0x3fb8aa3b, v1
	v_add_f32_e32 v3, v3, v3
	v_exp_f32_e32 v1, v1
	v_mul_f32_e32 v3, 0x3fb8aa3b, v3
	v_exp_f32_e32 v8, v3
	v_cvt_pk_bf16_f32 v3, v4, v5
	v_add_f32_e32 v1, 1.0, v1
	v_rcp_f32_e32 v4, v1
	v_add_f32_e32 v1, 1.0, v8
	v_lshlrev_b32_e32 v8, 16, v9
	v_and_b32_e32 v9, 0xffff0000, v9
	v_pk_fma_f32 v[8:9], v[38:39], v[8:9], v[30:31]
	v_rcp_f32_e32 v5, v1
	v_mul_f32_e32 v1, 0x3d372713, v8
	v_mul_f32_e32 v1, v8, v1
	v_mul_f32_e32 v10, 0x3d372713, v9
	v_fma_f32 v1, v8, v1, v8
	v_mul_f32_e32 v10, v9, v10
	v_mul_f32_e32 v1, 0x3f4c422a, v1
	v_fma_f32 v10, v9, v10, v9
	v_add_f32_e32 v1, v1, v1
	v_mul_f32_e32 v10, 0x3f4c422a, v10
	v_mul_f32_e32 v1, 0x3fb8aa3b, v1
	v_add_f32_e32 v10, v10, v10
	v_exp_f32_e32 v1, v1
	v_mul_f32_e32 v10, 0x3fb8aa3b, v10
	v_exp_f32_e32 v11, v10
	v_pk_fma_f32 v[4:5], v[4:5], 2.0, 1.0 op_sel_hi:[1,0,0] neg_lo:[1,0,0] neg_hi:[1,0,0]
	v_add_f32_e32 v1, 1.0, v1
	v_rcp_f32_e32 v10, v1
	v_add_f32_e32 v1, 1.0, v11
	v_rcp_f32_e32 v11, v1
	v_pk_mul_f32 v[6:7], v[6:7], 0.5 op_sel_hi:[1,0]
	v_pk_add_f32 v[4:5], v[4:5], 1.0 op_sel_hi:[1,0]
	v_pk_mul_f32 v[8:9], v[8:9], 0.5 op_sel_hi:[1,0]
	v_pk_mul_f32 v[4:5], v[6:7], v[4:5]
	v_pk_fma_f32 v[6:7], v[10:11], 2.0, 1.0 op_sel_hi:[1,0,0] neg_lo:[1,0,0] neg_hi:[1,0,0]
	v_ashrrev_i32_e32 v1, 31, v0
	v_pk_add_f32 v[6:7], v[6:7], 1.0 op_sel_hi:[1,0]
	v_cvt_pk_bf16_f32 v4, v4, v5
	v_pk_mul_f32 v[6:7], v[8:9], v[6:7]
	v_lshlrev_b64 v[0:1], 11, v[0:1]
	v_cvt_pk_bf16_f32 v5, v6, v7
	v_permlane32_swap_b32_e32 v2, v4
	s_nop 0
	v_permlane32_swap_b32_e32 v3, v5
	v_lshl_add_u64 v[0:1], v[156:157], 0, v[0:1]
	global_store_dwordx4 v[0:1], v[2:5], off
	s_cbranch_scc1 .LBB0_811
	s_waitcnt lgkmcnt(0)
	s_barrier
	s_waitcnt vmcnt(8)
	ds_write_b128 v165, v[104:107] offset:16384
	s_waitcnt vmcnt(7)
	ds_write_b128 v166, v[108:111] offset:16384
	s_waitcnt vmcnt(6)
	ds_write_b128 v167, v[112:115] offset:16384
	s_waitcnt vmcnt(5)
	ds_write_b128 v168, v[116:119] offset:16384
	s_waitcnt vmcnt(4)
	ds_write_b128 v169, v[120:123] offset:49664
	s_waitcnt lgkmcnt(0)
	s_barrier
	s_branch .Ls5_body
	s_nop 0
	s_nop 0
	s_nop 0
	s_nop 0
	s_nop 0
	s_nop 0
	s_nop 0
	s_nop 0
	s_nop 0
	s_nop 0
	s_nop 0
	s_nop 0

; #define S5O_PREFETCH(ctv) do { const u32x4* us_ = (const u32x4*)(U + ((size_t)g * S + (size_t)(ctv) * 1024) * 16); _Pragma("unroll") for (int i_ = 0; i_ < 4; ++i_) su[i_] = us_[tid + 512 * i_]; \
;         sh = ((const u32x4*)(HP + ((size_t)g * SNC + (ctv) * 32) * 128))[tid]; } while (0)
; __device__ __forceinline__ void s5_out_block2(LAS unsigned char* lds, const bf16* __restrict__ MLAG, const bf16* __restrict__ WC, const bf16* __restrict__ HP, const bf16* __restrict__ U, ...
;     ...
;         if (it < 3) S5O_PREFETCH(ct + 1);
.Ls5_body:
	s_or_b32 s23, s3, s2
	s_cmp_eq_u32 s3, 3
	s_cbranch_scc1 .LBB0_807
	s_add_i32 s26, s23, 1
	s_lshl_b32 s24, s26, 10
	s_add_u32 s24, s0, s24
	s_addc_u32 s25, s1, 0
	s_lshl_b64 s[24:25], s[24:25], 5
	s_add_u32 s24, s86, s24
	s_addc_u32 s25, s87, s25
	v_mov_b32_e32 v159, v153
	v_lshl_add_u64 v[0:1], s[24:25], 0, v[158:159]
	v_add_co_u32_e32 v2, vcc, s8, v0
	global_load_dwordx4 v[104:107], v158, s[24:25]
	s_nop 0
	v_addc_co_u32_e32 v3, vcc, 0, v1, vcc
	global_load_dwordx4 v[108:111], v[2:3], off
	global_load_dwordx4 v[112:115], v170, s[24:25]
	s_lshl_b32 s24, s26, 5
	s_add_u32 s24, s4, s24
	v_add_co_u32_e32 v0, vcc, s9, v0
	s_addc_u32 s25, s5, 0
	s_nop 0
	v_addc_co_u32_e32 v1, vcc, 0, v1, vcc
	s_lshl_b64 s[24:25], s[24:25], 8
	v_lshl_add_u64 v[2:3], v[154:155], 0, s[24:25]
	global_load_dwordx4 v[116:119], v[0:1], off
	global_load_dwordx4 v[120:123], v[2:3], off
